# diff-attn key loops: s_setprio 1 around the QK MFMA chain and around the P.V MFMA section (back to 0 after), as the GEMM template does around its MFMA blocks
# speedup vs baseline: 1.0612x; 1.0050x over previous
.LBB0_36:
	s_add_i32 s23, s10, -1
	s_and_b32 s23, s23, 1
	s_sub_i32 s26, s22, 63
	s_cmp_gt_u32 s26, s5
	s_cbranch_scc1 .LBB0_43
	s_mul_i32 s26, s23, 0x7400
	s_add_i32 s26, s26, 0
	s_cmp_le_u32 s22, s1
	v_add3_u32 v190, s26, v165, v172
	ds_read_b128 v[98:101], v190
	ds_read_b128 v[102:105], v190 offset:32
	ds_read_b128 v[106:109], v190 offset:64
	ds_read_b128 v[110:113], v190 offset:96
	ds_read_b128 v[240:243], v190 offset:4608
	ds_read_b128 v[244:247], v190 offset:4640
	ds_read_b128 v[214:217], v190 offset:4672
	ds_read_b128 v[190:193], v190 offset:4704
	s_setprio 1
	s_waitcnt lgkmcnt(7)
	v_mfma_f32_32x32x16_bf16 v[82:97], v[98:101], v[126:129], 0
	s_waitcnt lgkmcnt(6)
	v_mfma_f32_32x32x16_bf16 v[82:97], v[102:105], v[130:133], v[82:97]
	s_waitcnt lgkmcnt(5)
	v_mfma_f32_32x32x16_bf16 v[82:97], v[106:109], v[134:137], v[82:97]
	s_waitcnt lgkmcnt(4)
	v_mfma_f32_32x32x16_bf16 v[82:97], v[110:113], v[138:141], v[82:97]
	s_waitcnt lgkmcnt(3)
	v_mfma_f32_32x32x16_bf16 v[98:113], v[240:243], v[126:129], 0
	s_waitcnt lgkmcnt(2)
	v_mfma_f32_32x32x16_bf16 v[98:113], v[244:247], v[130:133], v[98:113]
	s_waitcnt lgkmcnt(1)
	v_mfma_f32_32x32x16_bf16 v[98:113], v[214:217], v[134:137], v[98:113]
	s_waitcnt lgkmcnt(0)
	v_mfma_f32_32x32x16_bf16 v[98:113], v[190:193], v[138:141], v[98:113]
	s_setprio 0
	s_cbranch_scc1 .LBB0_39
	v_add_u32_e32 v190, s22, v173
	v_subrev_u32_e32 v191, 63, v190
	v_cmp_le_i32_e32 vcc, v191, v179
	v_subrev_u32_e32 v192, 61, v190
	v_subrev_u32_e32 v190, 60, v190
	s_nop 5
	v_cndmask_b32_e32 v98, v220, v98, vcc
	v_cmp_lt_i32_e32 vcc, v191, v176
	s_nop 1
	v_cndmask_b32_e32 v83, v220, v83, vcc
	v_cmp_le_i32_e32 vcc, v191, v176
	s_nop 1
	v_cndmask_b32_e32 v82, v220, v82, vcc
	v_cmp_le_i32_e32 vcc, v191, v180
	s_nop 1
	v_cndmask_b32_e32 v99, v220, v99, vcc
	v_cmp_le_i32_e32 vcc, v192, v176
	s_nop 1
	v_cndmask_b32_e32 v84, v220, v84, vcc
	v_cmp_le_i32_e32 vcc, v191, v181
	s_nop 1
	v_cndmask_b32_e32 v100, v220, v100, vcc
	v_cmp_le_i32_e32 vcc, v190, v176
	s_nop 1
	v_cndmask_b32_e32 v85, v220, v85, vcc
	v_cmp_le_i32_e32 vcc, v191, v182
	s_nop 1
	v_cndmask_b32_e32 v101, v220, v101, vcc
	v_cmp_le_i32_e32 vcc, v191, v183
	s_nop 1
	v_cndmask_b32_e32 v86, v220, v86, vcc
	v_cmp_le_i32_e32 vcc, v191, v184
	s_nop 1
	v_cndmask_b32_e32 v102, v220, v102, vcc
	v_cmp_le_i32_e32 vcc, v191, v185
	s_nop 1
	v_cndmask_b32_e32 v87, v220, v87, vcc
	v_cmp_le_i32_e32 vcc, v191, v186
	s_nop 1
	v_cndmask_b32_e32 v103, v220, v103, vcc
	v_cmp_le_i32_e32 vcc, v191, v187
	s_nop 1
	v_cndmask_b32_e32 v88, v220, v88, vcc
	v_cmp_le_i32_e32 vcc, v191, v188
	s_nop 1
	v_cndmask_b32_e32 v104, v220, v104, vcc
	v_cmp_le_i32_e32 vcc, v191, v189
	s_nop 1
	v_cndmask_b32_e32 v89, v220, v89, vcc
	v_cmp_le_i32_e32 vcc, v191, v195
	s_nop 1
	v_cndmask_b32_e32 v105, v220, v105, vcc
	v_cmp_le_i32_e32 vcc, v191, v196
	s_nop 1
	v_cndmask_b32_e32 v90, v220, v90, vcc
	v_cmp_le_i32_e32 vcc, v191, v197
	s_nop 1
	v_cndmask_b32_e32 v106, v220, v106, vcc
	v_cmp_le_i32_e32 vcc, v191, v198
	s_nop 1
	v_cndmask_b32_e32 v91, v220, v91, vcc
	v_cmp_le_i32_e32 vcc, v191, v199
	s_nop 1
	v_cndmask_b32_e32 v107, v220, v107, vcc
	v_cmp_le_i32_e32 vcc, v191, v200
	s_nop 1
	v_cndmask_b32_e32 v92, v220, v92, vcc
	v_cmp_le_i32_e32 vcc, v191, v201
	s_nop 1
	v_cndmask_b32_e32 v108, v220, v108, vcc
	v_cmp_le_i32_e32 vcc, v191, v202
	s_nop 1
	v_cndmask_b32_e32 v93, v220, v93, vcc
	v_cmp_le_i32_e32 vcc, v191, v203
	s_nop 1
	v_cndmask_b32_e32 v109, v220, v109, vcc
	v_cmp_le_i32_e32 vcc, v191, v204
	s_nop 1
	v_cndmask_b32_e32 v94, v220, v94, vcc
	v_cmp_le_i32_e32 vcc, v191, v205
	s_nop 1
	v_cndmask_b32_e32 v110, v220, v110, vcc
	v_cmp_le_i32_e32 vcc, v191, v228
	s_nop 1
	v_cndmask_b32_e32 v95, v220, v95, vcc
	v_cmp_le_i32_e32 vcc, v191, v229
	s_nop 1
	v_cndmask_b32_e32 v111, v220, v111, vcc
	v_cmp_le_i32_e32 vcc, v191, v230
	s_nop 1
	v_cndmask_b32_e32 v96, v220, v96, vcc
	v_cmp_le_i32_e32 vcc, v191, v231
	s_nop 1
	v_cndmask_b32_e32 v112, v220, v112, vcc
	v_cmp_le_i32_e32 vcc, v191, v232
	s_nop 1
	v_cndmask_b32_e32 v97, v220, v97, vcc
	v_cmp_le_i32_e32 vcc, v191, v233
	s_nop 1
	v_cndmask_b32_e32 v113, v220, v113, vcc

.LBB0_45:
	v_add3_u32 v190, s26, v178, v177
	s_mov_b32 s78, s76
	s_mov_b32 s79, s76
	s_mov_b32 s77, s76
	ds_read_b64_tr_b16 v[240:241], v190 offset:9216
	ds_read_b64_tr_b16 v[242:243], v190 offset:11776
	ds_read_b64_tr_b16 v[244:245], v190 offset:9280
	ds_read_b64_tr_b16 v[246:247], v190 offset:11840
	ds_read_b64_tr_b16 v[214:215], v190 offset:9344
	ds_read_b64_tr_b16 v[216:217], v190 offset:11904
	v_sub_f32_e32 v82, v82, v238
	v_sub_f32_e32 v83, v83, v238
	v_sub_f32_e32 v84, v84, v238
	v_sub_f32_e32 v85, v85, v238
	v_sub_f32_e32 v86, v86, v238
	v_sub_f32_e32 v87, v87, v238
	v_sub_f32_e32 v88, v88, v238
	v_sub_f32_e32 v89, v89, v238
	v_exp_f32_e32 v82, v82
	v_exp_f32_e32 v83, v83
	v_exp_f32_e32 v84, v84
	v_exp_f32_e32 v85, v85
	v_exp_f32_e32 v86, v86
	v_exp_f32_e32 v87, v87
	v_exp_f32_e32 v88, v88
	v_exp_f32_e32 v89, v89
	v_cvt_pk_bf16_f32 v82, v82, v83
	v_cvt_pk_bf16_f32 v83, v84, v85
	v_cvt_pk_bf16_f32 v84, v86, v87
	v_cvt_pk_bf16_f32 v85, v88, v89
	v_mov_b64_e32 v[88:89], s[78:79]
	v_mov_b64_e32 v[86:87], s[76:77]
	s_setprio 1
	s_waitcnt lgkmcnt(4)
	v_mfma_f32_32x32x16_bf16 v[2:17], v[82:85], v[240:243], v[2:17]
	v_sub_f32_e32 v90, v90, v238
	v_sub_f32_e32 v91, v91, v238
	v_sub_f32_e32 v92, v92, v238
	v_sub_f32_e32 v93, v93, v238
	ds_read_b64_tr_b16 v[240:241], v190 offset:9408
	ds_read_b64_tr_b16 v[242:243], v190 offset:11968
	s_waitcnt lgkmcnt(4)
	v_mfma_f32_32x32x16_bf16 v[50:65], v[82:85], v[244:247], v[50:65]
	v_sub_f32_e32 v94, v94, v238
	v_sub_f32_e32 v95, v95, v238
	v_sub_f32_e32 v96, v96, v238
	v_sub_f32_e32 v97, v97, v238
	ds_read_b64_tr_b16 v[244:245], v190 offset:14336
	ds_read_b64_tr_b16 v[246:247], v190 offset:16896
	s_waitcnt lgkmcnt(4)
	v_mfma_f32_32x32x16_bf16 v[34:49], v[82:85], v[214:217], v[34:49]
	v_exp_f32_e32 v90, v90
	v_exp_f32_e32 v91, v91
	v_exp_f32_e32 v92, v92
	v_exp_f32_e32 v93, v93
	ds_read_b64_tr_b16 v[214:215], v190 offset:14400
	ds_read_b64_tr_b16 v[216:217], v190 offset:16960
	s_waitcnt lgkmcnt(4)
	v_mfma_f32_32x32x16_bf16 v[18:33], v[82:85], v[240:243], v[18:33]
	v_exp_f32_e32 v94, v94
	v_exp_f32_e32 v95, v95
	v_exp_f32_e32 v96, v96
	v_exp_f32_e32 v97, v97
	ds_read_b64_tr_b16 v[240:241], v190 offset:14464
	ds_read_b64_tr_b16 v[242:243], v190 offset:17024
	v_mfma_f32_32x32x16_bf16 v[66:81], v[82:85], v[86:89], v[66:81]
	v_cvt_pk_bf16_f32 v90, v90, v91
	v_cvt_pk_bf16_f32 v91, v92, v93
	v_cvt_pk_bf16_f32 v92, v94, v95
	v_cvt_pk_bf16_f32 v93, v96, v97
	s_nop 0
	s_waitcnt lgkmcnt(4)
	v_mfma_f32_32x32x16_bf16 v[2:17], v[90:93], v[244:247], v[2:17]
	v_sub_f32_e32 v98, v98, v238
	v_sub_f32_e32 v99, v99, v238
	v_sub_f32_e32 v100, v100, v238
	v_sub_f32_e32 v101, v101, v238
	ds_read_b64_tr_b16 v[244:245], v190 offset:14528
	ds_read_b64_tr_b16 v[246:247], v190 offset:17088
	s_waitcnt lgkmcnt(4)
	v_mfma_f32_32x32x16_bf16 v[50:65], v[90:93], v[214:217], v[50:65]
	v_sub_f32_e32 v102, v102, v238
	v_sub_f32_e32 v103, v103, v238
	v_sub_f32_e32 v104, v104, v238
	v_sub_f32_e32 v105, v105, v238
	ds_read_b64_tr_b16 v[214:215], v190 offset:19456
	ds_read_b64_tr_b16 v[216:217], v190 offset:22016
	s_waitcnt lgkmcnt(4)
	v_mfma_f32_32x32x16_bf16 v[34:49], v[90:93], v[240:243], v[34:49]
	v_exp_f32_e32 v98, v98
	v_exp_f32_e32 v99, v99
	v_exp_f32_e32 v100, v100
	v_exp_f32_e32 v101, v101
	ds_read_b64_tr_b16 v[240:241], v190 offset:19520
	ds_read_b64_tr_b16 v[242:243], v190 offset:22080
	s_waitcnt lgkmcnt(4)
	v_mfma_f32_32x32x16_bf16 v[18:33], v[90:93], v[244:247], v[18:33]
	v_exp_f32_e32 v102, v102
	v_exp_f32_e32 v103, v103
	v_exp_f32_e32 v104, v104
	v_exp_f32_e32 v105, v105
	ds_read_b64_tr_b16 v[244:245], v190 offset:19584
	ds_read_b64_tr_b16 v[246:247], v190 offset:22144
	v_mfma_f32_32x32x16_bf16 v[66:81], v[90:93], v[86:89], v[66:81]
	v_cvt_pk_bf16_f32 v98, v98, v99
	v_cvt_pk_bf16_f32 v99, v100, v101
	v_cvt_pk_bf16_f32 v100, v102, v103
	v_cvt_pk_bf16_f32 v101, v104, v105
	s_nop 0
	s_waitcnt lgkmcnt(4)
	v_mfma_f32_32x32x16_bf16 v[2:17], v[98:101], v[214:217], v[2:17]
	v_sub_f32_e32 v106, v106, v238
	v_sub_f32_e32 v107, v107, v238
	v_sub_f32_e32 v108, v108, v238
	v_sub_f32_e32 v109, v109, v238
	ds_read_b64_tr_b16 v[214:215], v190 offset:19648
	ds_read_b64_tr_b16 v[216:217], v190 offset:22208
	s_waitcnt lgkmcnt(4)
	v_mfma_f32_32x32x16_bf16 v[50:65], v[98:101], v[240:243], v[50:65]
	v_sub_f32_e32 v110, v110, v238
	v_sub_f32_e32 v111, v111, v238
	v_sub_f32_e32 v112, v112, v238
	v_sub_f32_e32 v113, v113, v238
	ds_read_b64_tr_b16 v[240:241], v190 offset:24576
	ds_read_b64_tr_b16 v[242:243], v190 offset:27136
	s_waitcnt lgkmcnt(4)
	v_mfma_f32_32x32x16_bf16 v[34:49], v[98:101], v[244:247], v[34:49]
	v_exp_f32_e32 v106, v106
	v_exp_f32_e32 v107, v107
	v_exp_f32_e32 v108, v108
	v_exp_f32_e32 v109, v109
	ds_read_b64_tr_b16 v[244:245], v190 offset:24640
	ds_read_b64_tr_b16 v[246:247], v190 offset:27200
	s_waitcnt lgkmcnt(4)
	v_mfma_f32_32x32x16_bf16 v[18:33], v[98:101], v[214:217], v[18:33]
	v_exp_f32_e32 v110, v110
	v_exp_f32_e32 v111, v111
	v_exp_f32_e32 v112, v112
	v_exp_f32_e32 v113, v113
	ds_read_b64_tr_b16 v[214:215], v190 offset:24704
	ds_read_b64_tr_b16 v[216:217], v190 offset:27264
	v_mfma_f32_32x32x16_bf16 v[66:81], v[98:101], v[86:89], v[66:81]
	v_cvt_pk_bf16_f32 v106, v106, v107
	v_cvt_pk_bf16_f32 v107, v108, v109
	v_cvt_pk_bf16_f32 v108, v110, v111
	v_cvt_pk_bf16_f32 v109, v112, v113
	s_nop 0
	s_waitcnt lgkmcnt(4)
	v_mfma_f32_32x32x16_bf16 v[2:17], v[106:109], v[240:243], v[2:17]
	ds_read_b64_tr_b16 v[240:241], v190 offset:24768
	ds_read_b64_tr_b16 v[242:243], v190 offset:27328
	s_waitcnt lgkmcnt(4)
	v_mfma_f32_32x32x16_bf16 v[50:65], v[106:109], v[244:247], v[50:65]
	s_waitcnt lgkmcnt(2)
	v_mfma_f32_32x32x16_bf16 v[34:49], v[106:109], v[214:217], v[34:49]
	s_waitcnt lgkmcnt(0)
	v_mfma_f32_32x32x16_bf16 v[18:33], v[106:109], v[240:243], v[18:33]
	v_mfma_f32_32x32x16_bf16 v[66:81], v[106:109], v[86:89], v[66:81]
	s_setprio 0
	s_movk_i32 s77, 0x110
	s_andn2_b64 vcc, exec, s[60:61]
	s_cbranch_vccnz .LBB0_47

.LBB0_51:
	s_add_i32 s23, s22, -1
	s_and_b32 s23, s23, 1
	s_sub_i32 s26, s10, 63
	s_cmp_gt_u32 s26, s5
	s_cbranch_scc1 .LBB0_58
	s_mul_i32 s26, s23, 0x7400
	s_add_i32 s26, s26, 0
	s_cmp_le_u32 s10, s1
	v_add3_u32 v152, s26, v165, v172
	ds_read_b128 v[98:101], v152
	ds_read_b128 v[102:105], v152 offset:32
	ds_read_b128 v[106:109], v152 offset:64
	ds_read_b128 v[110:113], v152 offset:96
	ds_read_b128 v[154:157], v152 offset:4608
	ds_read_b128 v[190:193], v152 offset:4640
	ds_read_b128 v[214:217], v152 offset:4672
	ds_read_b128 v[234:237], v152 offset:4704
	s_setprio 1
	s_waitcnt lgkmcnt(7)
	v_mfma_f32_32x32x16_bf16 v[82:97], v[98:101], v[114:117], 0
	s_waitcnt lgkmcnt(6)
	v_mfma_f32_32x32x16_bf16 v[82:97], v[102:105], v[118:121], v[82:97]
	s_waitcnt lgkmcnt(5)
	v_mfma_f32_32x32x16_bf16 v[82:97], v[106:109], v[126:129], v[82:97]
	s_waitcnt lgkmcnt(4)
	v_mfma_f32_32x32x16_bf16 v[82:97], v[110:113], v[130:133], v[82:97]
	s_waitcnt lgkmcnt(3)
	v_mfma_f32_32x32x16_bf16 v[98:113], v[154:157], v[114:117], 0
	s_waitcnt lgkmcnt(2)
	v_mfma_f32_32x32x16_bf16 v[98:113], v[190:193], v[118:121], v[98:113]
	s_waitcnt lgkmcnt(1)
	v_mfma_f32_32x32x16_bf16 v[98:113], v[214:217], v[126:129], v[98:113]
	s_waitcnt lgkmcnt(0)
	v_mfma_f32_32x32x16_bf16 v[98:113], v[234:237], v[130:133], v[98:113]
	s_setprio 0
	s_cbranch_scc1 .LBB0_54
	v_add_u32_e32 v152, s10, v173
	v_subrev_u32_e32 v154, 63, v152
	v_cmp_le_i32_e32 vcc, v154, v179
	v_subrev_u32_e32 v155, 61, v152
	v_subrev_u32_e32 v152, 60, v152
	s_nop 5
	v_cndmask_b32_e32 v98, v220, v98, vcc
	v_cmp_lt_i32_e32 vcc, v154, v176
	s_nop 1
	v_cndmask_b32_e32 v83, v220, v83, vcc
	v_cmp_le_i32_e32 vcc, v154, v176
	s_nop 1
	v_cndmask_b32_e32 v82, v220, v82, vcc
	v_cmp_le_i32_e32 vcc, v154, v180
	s_nop 1
	v_cndmask_b32_e32 v99, v220, v99, vcc
	v_cmp_le_i32_e32 vcc, v155, v176
	s_nop 1
	v_cndmask_b32_e32 v84, v220, v84, vcc
	v_cmp_le_i32_e32 vcc, v154, v181
	s_nop 1
	v_cndmask_b32_e32 v100, v220, v100, vcc
	v_cmp_le_i32_e32 vcc, v152, v176
	s_nop 1
	v_cndmask_b32_e32 v85, v220, v85, vcc
	v_cmp_le_i32_e32 vcc, v154, v182
	s_nop 1
	v_cndmask_b32_e32 v101, v220, v101, vcc
	v_cmp_le_i32_e32 vcc, v154, v183
	s_nop 1
	v_cndmask_b32_e32 v86, v220, v86, vcc
	v_cmp_le_i32_e32 vcc, v154, v184
	s_nop 1
	v_cndmask_b32_e32 v102, v220, v102, vcc
	v_cmp_le_i32_e32 vcc, v154, v185
	s_nop 1
	v_cndmask_b32_e32 v87, v220, v87, vcc
	v_cmp_le_i32_e32 vcc, v154, v186
	s_nop 1
	v_cndmask_b32_e32 v103, v220, v103, vcc
	v_cmp_le_i32_e32 vcc, v154, v187
	s_nop 1
	v_cndmask_b32_e32 v88, v220, v88, vcc
	v_cmp_le_i32_e32 vcc, v154, v188
	s_nop 1
	v_cndmask_b32_e32 v104, v220, v104, vcc
	v_cmp_le_i32_e32 vcc, v154, v189
	s_nop 1
	v_cndmask_b32_e32 v89, v220, v89, vcc
	v_cmp_le_i32_e32 vcc, v154, v195
	s_nop 1
	v_cndmask_b32_e32 v105, v220, v105, vcc
	v_cmp_le_i32_e32 vcc, v154, v196
	s_nop 1
	v_cndmask_b32_e32 v90, v220, v90, vcc
	v_cmp_le_i32_e32 vcc, v154, v197
	s_nop 1
	v_cndmask_b32_e32 v106, v220, v106, vcc
	v_cmp_le_i32_e32 vcc, v154, v198
	s_nop 1
	v_cndmask_b32_e32 v91, v220, v91, vcc
	v_cmp_le_i32_e32 vcc, v154, v199
	s_nop 1
	v_cndmask_b32_e32 v107, v220, v107, vcc
	v_cmp_le_i32_e32 vcc, v154, v200
	s_nop 1
	v_cndmask_b32_e32 v92, v220, v92, vcc
	v_cmp_le_i32_e32 vcc, v154, v201
	s_nop 1
	v_cndmask_b32_e32 v108, v220, v108, vcc
	v_cmp_le_i32_e32 vcc, v154, v202
	s_nop 1
	v_cndmask_b32_e32 v93, v220, v93, vcc
	v_cmp_le_i32_e32 vcc, v154, v203
	s_nop 1
	v_cndmask_b32_e32 v109, v220, v109, vcc
	v_cmp_le_i32_e32 vcc, v154, v204
	s_nop 1
	v_cndmask_b32_e32 v94, v220, v94, vcc
	v_cmp_le_i32_e32 vcc, v154, v205
	s_nop 1
	v_cndmask_b32_e32 v110, v220, v110, vcc
	v_cmp_le_i32_e32 vcc, v154, v228
	s_nop 1
	v_cndmask_b32_e32 v95, v220, v95, vcc
	v_cmp_le_i32_e32 vcc, v154, v229
	s_nop 1
	v_cndmask_b32_e32 v111, v220, v111, vcc
	v_cmp_le_i32_e32 vcc, v154, v230
	s_nop 1
	v_cndmask_b32_e32 v96, v220, v96, vcc
	v_cmp_le_i32_e32 vcc, v154, v231
	s_nop 1
	v_cndmask_b32_e32 v112, v220, v112, vcc
	v_cmp_le_i32_e32 vcc, v154, v232
	s_nop 1
	v_cndmask_b32_e32 v97, v220, v97, vcc
	v_cmp_le_i32_e32 vcc, v154, v233
	s_nop 1
	v_cndmask_b32_e32 v113, v220, v113, vcc

.LBB0_60:
	v_add3_u32 v153, s26, v178, v177
	s_mov_b32 s78, s76
	s_mov_b32 s79, s76
	s_mov_b32 s77, s76
	ds_read_b64_tr_b16 v[154:155], v153 offset:9216
	ds_read_b64_tr_b16 v[156:157], v153 offset:11776
	ds_read_b64_tr_b16 v[190:191], v153 offset:9280
	ds_read_b64_tr_b16 v[192:193], v153 offset:11840
	ds_read_b64_tr_b16 v[214:215], v153 offset:9344
	ds_read_b64_tr_b16 v[216:217], v153 offset:11904
	ds_read_b64_tr_b16 v[234:235], v153 offset:9408
	ds_read_b64_tr_b16 v[236:237], v153 offset:11968
	v_sub_f32_e32 v82, v82, v152
	v_sub_f32_e32 v83, v83, v152
	v_sub_f32_e32 v84, v84, v152
	v_sub_f32_e32 v85, v85, v152
	v_sub_f32_e32 v86, v86, v152
	v_sub_f32_e32 v87, v87, v152
	v_sub_f32_e32 v88, v88, v152
	v_sub_f32_e32 v89, v89, v152
	v_exp_f32_e32 v82, v82
	v_exp_f32_e32 v83, v83
	v_exp_f32_e32 v84, v84
	v_exp_f32_e32 v85, v85
	v_exp_f32_e32 v86, v86
	v_exp_f32_e32 v87, v87
	v_exp_f32_e32 v88, v88
	v_exp_f32_e32 v89, v89
	v_cvt_pk_bf16_f32 v82, v82, v83
	v_cvt_pk_bf16_f32 v83, v84, v85
	v_cvt_pk_bf16_f32 v84, v86, v87
	v_cvt_pk_bf16_f32 v85, v88, v89
	v_mov_b64_e32 v[88:89], s[78:79]
	v_mov_b64_e32 v[86:87], s[76:77]
	s_setprio 1
	s_waitcnt lgkmcnt(6)
	v_mfma_f32_32x32x16_bf16 v[2:17], v[82:85], v[154:157], v[2:17]
	v_sub_f32_e32 v90, v90, v152
	v_sub_f32_e32 v91, v91, v152
	v_sub_f32_e32 v92, v92, v152
	v_sub_f32_e32 v93, v93, v152
	ds_read_b64_tr_b16 v[154:155], v153 offset:14336
	ds_read_b64_tr_b16 v[156:157], v153 offset:16896
	s_waitcnt lgkmcnt(6)
	v_mfma_f32_32x32x16_bf16 v[50:65], v[82:85], v[190:193], v[50:65]
	v_sub_f32_e32 v94, v94, v152
	v_sub_f32_e32 v95, v95, v152
	v_sub_f32_e32 v96, v96, v152
	v_sub_f32_e32 v97, v97, v152
	ds_read_b64_tr_b16 v[190:191], v153 offset:14400
	ds_read_b64_tr_b16 v[192:193], v153 offset:16960
	s_waitcnt lgkmcnt(6)
	v_mfma_f32_32x32x16_bf16 v[18:33], v[82:85], v[214:217], v[18:33]
	v_exp_f32_e32 v90, v90
	v_exp_f32_e32 v91, v91
	v_exp_f32_e32 v92, v92
	v_exp_f32_e32 v93, v93
	ds_read_b64_tr_b16 v[214:215], v153 offset:14464
	ds_read_b64_tr_b16 v[216:217], v153 offset:17024
	s_waitcnt lgkmcnt(6)
	v_mfma_f32_32x32x16_bf16 v[34:49], v[82:85], v[234:237], v[34:49]
	v_exp_f32_e32 v94, v94
	v_exp_f32_e32 v95, v95
	v_exp_f32_e32 v96, v96
	v_exp_f32_e32 v97, v97
	ds_read_b64_tr_b16 v[234:235], v153 offset:14528
	ds_read_b64_tr_b16 v[236:237], v153 offset:17088
	v_mfma_f32_32x32x16_bf16 v[66:81], v[82:85], v[86:89], v[66:81]
	v_cvt_pk_bf16_f32 v90, v90, v91
	v_cvt_pk_bf16_f32 v91, v92, v93
	v_cvt_pk_bf16_f32 v92, v94, v95
	v_cvt_pk_bf16_f32 v93, v96, v97
	s_nop 0
	s_waitcnt lgkmcnt(6)
	v_mfma_f32_32x32x16_bf16 v[2:17], v[90:93], v[154:157], v[2:17]
	v_sub_f32_e32 v98, v98, v152
	v_sub_f32_e32 v99, v99, v152
	v_sub_f32_e32 v100, v100, v152
	v_sub_f32_e32 v101, v101, v152
	ds_read_b64_tr_b16 v[154:155], v153 offset:19456
	ds_read_b64_tr_b16 v[156:157], v153 offset:22016
	s_waitcnt lgkmcnt(6)
	v_mfma_f32_32x32x16_bf16 v[50:65], v[90:93], v[190:193], v[50:65]
	v_sub_f32_e32 v102, v102, v152
	v_sub_f32_e32 v103, v103, v152
	v_sub_f32_e32 v104, v104, v152
	v_sub_f32_e32 v105, v105, v152
	ds_read_b64_tr_b16 v[190:191], v153 offset:19520
	ds_read_b64_tr_b16 v[192:193], v153 offset:22080
	s_waitcnt lgkmcnt(6)
	v_mfma_f32_32x32x16_bf16 v[18:33], v[90:93], v[214:217], v[18:33]
	v_exp_f32_e32 v98, v98
	v_exp_f32_e32 v99, v99
	v_exp_f32_e32 v100, v100
	v_exp_f32_e32 v101, v101
	ds_read_b64_tr_b16 v[214:215], v153 offset:19584
	ds_read_b64_tr_b16 v[216:217], v153 offset:22144
	s_waitcnt lgkmcnt(6)
	v_mfma_f32_32x32x16_bf16 v[34:49], v[90:93], v[234:237], v[34:49]
	v_exp_f32_e32 v102, v102
	v_exp_f32_e32 v103, v103
	v_exp_f32_e32 v104, v104
	v_exp_f32_e32 v105, v105
	ds_read_b64_tr_b16 v[234:235], v153 offset:19648
	ds_read_b64_tr_b16 v[236:237], v153 offset:22208
	v_mfma_f32_32x32x16_bf16 v[66:81], v[90:93], v[86:89], v[66:81]
	v_cvt_pk_bf16_f32 v98, v98, v99
	v_cvt_pk_bf16_f32 v99, v100, v101
	v_cvt_pk_bf16_f32 v100, v102, v103
	v_cvt_pk_bf16_f32 v101, v104, v105
	s_nop 0
	s_waitcnt lgkmcnt(6)
	v_mfma_f32_32x32x16_bf16 v[2:17], v[98:101], v[154:157], v[2:17]
	v_sub_f32_e32 v106, v106, v152
	v_sub_f32_e32 v107, v107, v152
	v_sub_f32_e32 v108, v108, v152
	v_sub_f32_e32 v109, v109, v152
	ds_read_b64_tr_b16 v[154:155], v153 offset:24576
	ds_read_b64_tr_b16 v[156:157], v153 offset:27136
	s_waitcnt lgkmcnt(6)
	v_mfma_f32_32x32x16_bf16 v[50:65], v[98:101], v[190:193], v[50:65]
	v_sub_f32_e32 v110, v110, v152
	v_sub_f32_e32 v111, v111, v152
	v_sub_f32_e32 v112, v112, v152
	v_sub_f32_e32 v113, v113, v152
	ds_read_b64_tr_b16 v[190:191], v153 offset:24640
	ds_read_b64_tr_b16 v[192:193], v153 offset:27200
	s_waitcnt lgkmcnt(6)
	v_mfma_f32_32x32x16_bf16 v[18:33], v[98:101], v[214:217], v[18:33]
	v_exp_f32_e32 v106, v106
	v_exp_f32_e32 v107, v107
	v_exp_f32_e32 v108, v108
	v_exp_f32_e32 v109, v109
	ds_read_b64_tr_b16 v[214:215], v153 offset:24704
	ds_read_b64_tr_b16 v[216:217], v153 offset:27264
	s_waitcnt lgkmcnt(6)
	v_mfma_f32_32x32x16_bf16 v[34:49], v[98:101], v[234:237], v[34:49]
	v_exp_f32_e32 v110, v110
	v_exp_f32_e32 v111, v111
	v_exp_f32_e32 v112, v112
	v_exp_f32_e32 v113, v113
	ds_read_b64_tr_b16 v[234:235], v153 offset:24768
	ds_read_b64_tr_b16 v[236:237], v153 offset:27328
	v_mfma_f32_32x32x16_bf16 v[66:81], v[98:101], v[86:89], v[66:81]
	v_cvt_pk_bf16_f32 v106, v106, v107
	v_cvt_pk_bf16_f32 v107, v108, v109
	v_cvt_pk_bf16_f32 v108, v110, v111
	v_cvt_pk_bf16_f32 v109, v112, v113
	s_nop 0
	s_waitcnt lgkmcnt(6)
	v_mfma_f32_32x32x16_bf16 v[2:17], v[106:109], v[154:157], v[2:17]
	s_waitcnt lgkmcnt(4)
	v_mfma_f32_32x32x16_bf16 v[50:65], v[106:109], v[190:193], v[50:65]
	s_waitcnt lgkmcnt(2)
	v_mfma_f32_32x32x16_bf16 v[18:33], v[106:109], v[214:217], v[18:33]
	s_waitcnt lgkmcnt(0)
	v_mfma_f32_32x32x16_bf16 v[34:49], v[106:109], v[234:237], v[34:49]
	v_mfma_f32_32x32x16_bf16 v[66:81], v[106:109], v[86:89], v[66:81]
	s_setprio 0
	s_movk_i32 s77, 0x110
	s_andn2_b64 vcc, exec, s[62:63]
	s_cbranch_vccnz .LBB0_62

.LBB0_66:
	s_add_i32 s23, s4, -1
	s_and_b32 s23, s23, 1
	s_cmp_gt_u32 s22, s11
	s_cbranch_scc1 .LBB0_73
	s_mul_i32 s26, s23, 0x7400
	s_add_i32 s26, s26, 0
	s_add_i32 s30, s22, 63
	s_cmp_le_u32 s30, s1
	v_add3_u32 v206, s26, v177, v178
	ds_read_b128 v[98:101], v206
	ds_read_b128 v[102:105], v206 offset:32
	ds_read_b128 v[106:109], v206 offset:64
	ds_read_b128 v[110:113], v206 offset:96
	ds_read_b128 v[190:193], v206 offset:4608
	ds_read_b128 v[214:217], v206 offset:4640
	ds_read_b128 v[244:247], v206 offset:4672
	ds_read_b128 v[206:209], v206 offset:4704
	s_setprio 1
	s_waitcnt lgkmcnt(7)
	v_mfma_f32_32x32x16_bf16 v[82:97], v[98:101], v[126:129], 0
	s_waitcnt lgkmcnt(6)
	v_mfma_f32_32x32x16_bf16 v[82:97], v[102:105], v[130:133], v[82:97]
	s_waitcnt lgkmcnt(5)
	v_mfma_f32_32x32x16_bf16 v[82:97], v[106:109], v[134:137], v[82:97]
	s_waitcnt lgkmcnt(4)
	v_mfma_f32_32x32x16_bf16 v[82:97], v[110:113], v[138:141], v[82:97]
	s_waitcnt lgkmcnt(3)
	v_mfma_f32_32x32x16_bf16 v[98:113], v[190:193], v[126:129], 0
	s_waitcnt lgkmcnt(2)
	v_mfma_f32_32x32x16_bf16 v[98:113], v[214:217], v[130:133], v[98:113]
	s_waitcnt lgkmcnt(1)
	v_mfma_f32_32x32x16_bf16 v[98:113], v[244:247], v[134:137], v[98:113]
	s_waitcnt lgkmcnt(0)
	v_mfma_f32_32x32x16_bf16 v[98:113], v[206:209], v[138:141], v[98:113]
	s_setprio 0
	s_cbranch_scc1 .LBB0_69
	v_add_u32_e32 v190, s22, v179
	v_cmp_le_i32_e32 vcc, v190, v183
	v_add_u32_e32 v191, 2, v190
	s_nop 7
	v_cndmask_b32_e32 v98, v220, v98, vcc
	v_cmp_lt_i32_e32 vcc, v190, v173
	s_nop 1
	v_cndmask_b32_e32 v83, v220, v83, vcc
	v_cmp_le_i32_e32 vcc, v190, v173
	s_nop 1
	v_cndmask_b32_e32 v82, v220, v82, vcc
	v_cmp_le_i32_e32 vcc, v190, v184
	s_nop 1
	v_cndmask_b32_e32 v99, v220, v99, vcc
	v_cmp_le_i32_e32 vcc, v191, v173
	v_add_u32_e32 v191, 3, v190
	s_nop 0
	v_cndmask_b32_e32 v84, v220, v84, vcc
	v_cmp_le_i32_e32 vcc, v190, v185
	s_nop 1
	v_cndmask_b32_e32 v100, v220, v100, vcc
	v_cmp_le_i32_e32 vcc, v191, v173
	s_nop 1
	v_cndmask_b32_e32 v85, v220, v85, vcc
	v_cmp_le_i32_e32 vcc, v190, v186
	s_nop 1
	v_cndmask_b32_e32 v101, v220, v101, vcc
	v_cmp_le_i32_e32 vcc, v190, v187
	s_nop 1
	v_cndmask_b32_e32 v86, v220, v86, vcc
	v_cmp_le_i32_e32 vcc, v190, v188
	s_nop 1
	v_cndmask_b32_e32 v102, v220, v102, vcc
	v_cmp_le_i32_e32 vcc, v190, v189
	s_nop 1
	v_cndmask_b32_e32 v87, v220, v87, vcc
	v_cmp_le_i32_e32 vcc, v190, v195
	s_nop 1
	v_cndmask_b32_e32 v103, v220, v103, vcc
	v_cmp_le_i32_e32 vcc, v190, v196
	s_nop 1
	v_cndmask_b32_e32 v88, v220, v88, vcc
	v_cmp_le_i32_e32 vcc, v190, v197
	s_nop 1
	v_cndmask_b32_e32 v104, v220, v104, vcc
	v_cmp_le_i32_e32 vcc, v190, v198
	s_nop 1
	v_cndmask_b32_e32 v89, v220, v89, vcc
	v_cmp_le_i32_e32 vcc, v190, v199
	s_nop 1
	v_cndmask_b32_e32 v105, v220, v105, vcc
	v_cmp_le_i32_e32 vcc, v190, v200
	s_nop 1
	v_cndmask_b32_e32 v90, v220, v90, vcc
	v_cmp_le_i32_e32 vcc, v190, v201
	s_nop 1
	v_cndmask_b32_e32 v106, v220, v106, vcc
	v_cmp_le_i32_e32 vcc, v190, v202
	s_nop 1
	v_cndmask_b32_e32 v91, v220, v91, vcc
	v_cmp_le_i32_e32 vcc, v190, v203
	s_nop 1
	v_cndmask_b32_e32 v107, v220, v107, vcc
	v_cmp_le_i32_e32 vcc, v190, v204
	s_nop 1
	v_cndmask_b32_e32 v92, v220, v92, vcc
	v_cmp_le_i32_e32 vcc, v190, v205
	s_nop 1
	v_cndmask_b32_e32 v108, v220, v108, vcc
	v_cmp_le_i32_e32 vcc, v190, v228
	s_nop 1
	v_cndmask_b32_e32 v93, v220, v93, vcc
	v_cmp_le_i32_e32 vcc, v190, v229
	s_nop 1
	v_cndmask_b32_e32 v109, v220, v109, vcc
	v_cmp_le_i32_e32 vcc, v190, v230
	s_nop 1
	v_cndmask_b32_e32 v94, v220, v94, vcc
	v_cmp_le_i32_e32 vcc, v190, v231
	s_nop 1
	v_cndmask_b32_e32 v110, v220, v110, vcc
	v_cmp_le_i32_e32 vcc, v190, v232
	s_nop 1
	v_cndmask_b32_e32 v95, v220, v95, vcc
	v_cmp_le_i32_e32 vcc, v190, v233
	s_nop 1
	v_cndmask_b32_e32 v111, v220, v111, vcc
	v_cmp_le_i32_e32 vcc, v190, v234
	s_nop 1
	v_cndmask_b32_e32 v96, v220, v96, vcc
	v_cmp_le_i32_e32 vcc, v190, v235
	s_nop 1
	v_cndmask_b32_e32 v112, v220, v112, vcc
	v_cmp_le_i32_e32 vcc, v190, v236
	s_nop 1
	v_cndmask_b32_e32 v97, v220, v97, vcc
	v_cmp_le_i32_e32 vcc, v190, v237
	s_nop 1
	v_cndmask_b32_e32 v113, v220, v113, vcc

.LBB0_75:
	v_add3_u32 v190, s26, v182, v181
	s_mov_b32 s78, s76
	s_mov_b32 s79, s76
	s_mov_b32 s77, s76
	ds_read_b64_tr_b16 v[214:215], v190 offset:9216
	ds_read_b64_tr_b16 v[216:217], v190 offset:11776
	ds_read_b64_tr_b16 v[244:245], v190 offset:9280
	ds_read_b64_tr_b16 v[246:247], v190 offset:11840
	ds_read_b64_tr_b16 v[206:207], v190 offset:9344
	ds_read_b64_tr_b16 v[208:209], v190 offset:11904
	v_sub_f32_e32 v82, v82, v242
	v_sub_f32_e32 v83, v83, v242
	v_sub_f32_e32 v84, v84, v242
	v_sub_f32_e32 v85, v85, v242
	v_sub_f32_e32 v86, v86, v242
	v_sub_f32_e32 v87, v87, v242
	v_sub_f32_e32 v88, v88, v242
	v_sub_f32_e32 v89, v89, v242
	v_exp_f32_e32 v82, v82
	v_exp_f32_e32 v83, v83
	v_exp_f32_e32 v84, v84
	v_exp_f32_e32 v85, v85
	v_exp_f32_e32 v86, v86
	v_exp_f32_e32 v87, v87
	v_exp_f32_e32 v88, v88
	v_exp_f32_e32 v89, v89
	v_cvt_pk_bf16_f32 v82, v82, v83
	v_cvt_pk_bf16_f32 v83, v84, v85
	v_cvt_pk_bf16_f32 v84, v86, v87
	v_cvt_pk_bf16_f32 v85, v88, v89
	v_mov_b64_e32 v[88:89], s[78:79]
	v_mov_b64_e32 v[86:87], s[76:77]
	s_setprio 1
	s_waitcnt lgkmcnt(4)
	v_mfma_f32_32x32x16_bf16 v[2:17], v[82:85], v[214:217], v[2:17]
	v_sub_f32_e32 v90, v90, v242
	v_sub_f32_e32 v91, v91, v242
	v_sub_f32_e32 v92, v92, v242
	v_sub_f32_e32 v93, v93, v242
	ds_read_b64_tr_b16 v[214:215], v190 offset:9408
	ds_read_b64_tr_b16 v[216:217], v190 offset:11968
	s_waitcnt lgkmcnt(4)
	v_mfma_f32_32x32x16_bf16 v[50:65], v[82:85], v[244:247], v[50:65]
	v_sub_f32_e32 v94, v94, v242
	v_sub_f32_e32 v95, v95, v242
	v_sub_f32_e32 v96, v96, v242
	v_sub_f32_e32 v97, v97, v242
	ds_read_b64_tr_b16 v[244:245], v190 offset:14336
	ds_read_b64_tr_b16 v[246:247], v190 offset:16896
	s_waitcnt lgkmcnt(4)
	v_mfma_f32_32x32x16_bf16 v[34:49], v[82:85], v[206:209], v[34:49]
	v_exp_f32_e32 v90, v90
	v_exp_f32_e32 v91, v91
	v_exp_f32_e32 v92, v92
	v_exp_f32_e32 v93, v93
	ds_read_b64_tr_b16 v[206:207], v190 offset:14400
	ds_read_b64_tr_b16 v[208:209], v190 offset:16960
	s_waitcnt lgkmcnt(4)
	v_mfma_f32_32x32x16_bf16 v[18:33], v[82:85], v[214:217], v[18:33]
	v_exp_f32_e32 v94, v94
	v_exp_f32_e32 v95, v95
	v_exp_f32_e32 v96, v96
	v_exp_f32_e32 v97, v97
	ds_read_b64_tr_b16 v[214:215], v190 offset:14464
	ds_read_b64_tr_b16 v[216:217], v190 offset:17024
	v_mfma_f32_32x32x16_bf16 v[66:81], v[82:85], v[86:89], v[66:81]
	v_cvt_pk_bf16_f32 v90, v90, v91
	v_cvt_pk_bf16_f32 v91, v92, v93
	v_cvt_pk_bf16_f32 v92, v94, v95
	v_cvt_pk_bf16_f32 v93, v96, v97
	s_nop 0
	s_waitcnt lgkmcnt(4)
	v_mfma_f32_32x32x16_bf16 v[2:17], v[90:93], v[244:247], v[2:17]
	v_sub_f32_e32 v98, v98, v242
	v_sub_f32_e32 v99, v99, v242
	v_sub_f32_e32 v100, v100, v242
	v_sub_f32_e32 v101, v101, v242
	ds_read_b64_tr_b16 v[244:245], v190 offset:14528
	ds_read_b64_tr_b16 v[246:247], v190 offset:17088
	s_waitcnt lgkmcnt(4)
	v_mfma_f32_32x32x16_bf16 v[50:65], v[90:93], v[206:209], v[50:65]
	v_sub_f32_e32 v102, v102, v242
	v_sub_f32_e32 v103, v103, v242
	v_sub_f32_e32 v104, v104, v242
	v_sub_f32_e32 v105, v105, v242
	ds_read_b64_tr_b16 v[206:207], v190 offset:19456
	ds_read_b64_tr_b16 v[208:209], v190 offset:22016
	s_waitcnt lgkmcnt(4)
	v_mfma_f32_32x32x16_bf16 v[34:49], v[90:93], v[214:217], v[34:49]
	v_exp_f32_e32 v98, v98
	v_exp_f32_e32 v99, v99
	v_exp_f32_e32 v100, v100
	v_exp_f32_e32 v101, v101
	ds_read_b64_tr_b16 v[214:215], v190 offset:19520
	ds_read_b64_tr_b16 v[216:217], v190 offset:22080
	s_waitcnt lgkmcnt(4)
	v_mfma_f32_32x32x16_bf16 v[18:33], v[90:93], v[244:247], v[18:33]
	v_exp_f32_e32 v102, v102
	v_exp_f32_e32 v103, v103
	v_exp_f32_e32 v104, v104
	v_exp_f32_e32 v105, v105
	ds_read_b64_tr_b16 v[244:245], v190 offset:19584
	ds_read_b64_tr_b16 v[246:247], v190 offset:22144
	v_mfma_f32_32x32x16_bf16 v[66:81], v[90:93], v[86:89], v[66:81]
	v_cvt_pk_bf16_f32 v98, v98, v99
	v_cvt_pk_bf16_f32 v99, v100, v101
	v_cvt_pk_bf16_f32 v100, v102, v103
	v_cvt_pk_bf16_f32 v101, v104, v105
	s_nop 0
	s_waitcnt lgkmcnt(4)
	v_mfma_f32_32x32x16_bf16 v[2:17], v[98:101], v[206:209], v[2:17]
	v_sub_f32_e32 v106, v106, v242
	v_sub_f32_e32 v107, v107, v242
	v_sub_f32_e32 v108, v108, v242
	v_sub_f32_e32 v109, v109, v242
	ds_read_b64_tr_b16 v[206:207], v190 offset:19648
	ds_read_b64_tr_b16 v[208:209], v190 offset:22208
	s_waitcnt lgkmcnt(4)
	v_mfma_f32_32x32x16_bf16 v[50:65], v[98:101], v[214:217], v[50:65]
	v_sub_f32_e32 v110, v110, v242
	v_sub_f32_e32 v111, v111, v242
	v_sub_f32_e32 v112, v112, v242
	v_sub_f32_e32 v113, v113, v242
	ds_read_b64_tr_b16 v[214:215], v190 offset:24576
	ds_read_b64_tr_b16 v[216:217], v190 offset:27136
	s_waitcnt lgkmcnt(4)
	v_mfma_f32_32x32x16_bf16 v[34:49], v[98:101], v[244:247], v[34:49]
	v_exp_f32_e32 v106, v106
	v_exp_f32_e32 v107, v107
	v_exp_f32_e32 v108, v108
	v_exp_f32_e32 v109, v109
	ds_read_b64_tr_b16 v[244:245], v190 offset:24640
	ds_read_b64_tr_b16 v[246:247], v190 offset:27200
	s_waitcnt lgkmcnt(4)
	v_mfma_f32_32x32x16_bf16 v[18:33], v[98:101], v[206:209], v[18:33]
	v_exp_f32_e32 v110, v110
	v_exp_f32_e32 v111, v111
	v_exp_f32_e32 v112, v112
	v_exp_f32_e32 v113, v113
	ds_read_b64_tr_b16 v[206:207], v190 offset:24704
	ds_read_b64_tr_b16 v[208:209], v190 offset:27264
	v_mfma_f32_32x32x16_bf16 v[66:81], v[98:101], v[86:89], v[66:81]
	v_cvt_pk_bf16_f32 v106, v106, v107
	v_cvt_pk_bf16_f32 v107, v108, v109
	v_cvt_pk_bf16_f32 v108, v110, v111
	v_cvt_pk_bf16_f32 v109, v112, v113
	s_nop 0
	s_waitcnt lgkmcnt(4)
	v_mfma_f32_32x32x16_bf16 v[2:17], v[106:109], v[214:217], v[2:17]
	ds_read_b64_tr_b16 v[214:215], v190 offset:24768
	ds_read_b64_tr_b16 v[216:217], v190 offset:27328
	s_waitcnt lgkmcnt(4)
	v_mfma_f32_32x32x16_bf16 v[50:65], v[106:109], v[244:247], v[50:65]
	s_waitcnt lgkmcnt(2)
	v_mfma_f32_32x32x16_bf16 v[34:49], v[106:109], v[206:209], v[34:49]
	s_waitcnt lgkmcnt(0)
	v_mfma_f32_32x32x16_bf16 v[18:33], v[106:109], v[214:217], v[18:33]
	v_mfma_f32_32x32x16_bf16 v[66:81], v[106:109], v[86:89], v[66:81]
	s_setprio 0
	s_movk_i32 s77, 0x110
	s_andn2_b64 vcc, exec, s[28:29]
	s_cbranch_vccnz .LBB0_77

.LBB0_81:
	s_add_i32 s23, s22, -1
	s_and_b32 s23, s23, 1
	s_cmp_gt_u32 s4, s11
	s_cbranch_scc1 .LBB0_88
	s_mul_i32 s26, s23, 0x7400
	s_add_i32 s26, s26, 0
	s_add_i32 s30, s4, 63
	s_cmp_le_u32 s30, s1
	v_add3_u32 v152, s26, v177, v178
	ds_read_b128 v[98:101], v152
	ds_read_b128 v[102:105], v152 offset:32
	ds_read_b128 v[106:109], v152 offset:64
	ds_read_b128 v[110:113], v152 offset:96
	ds_read_b128 v[154:157], v152 offset:4608
	ds_read_b128 v[162:165], v152 offset:4640
	ds_read_b128 v[190:193], v152 offset:4672
	ds_read_b128 v[206:209], v152 offset:4704
	s_setprio 1
	s_waitcnt lgkmcnt(7)
	v_mfma_f32_32x32x16_bf16 v[82:97], v[98:101], v[118:121], 0
	s_waitcnt lgkmcnt(6)
	v_mfma_f32_32x32x16_bf16 v[82:97], v[102:105], v[122:125], v[82:97]
	s_waitcnt lgkmcnt(5)
	v_mfma_f32_32x32x16_bf16 v[82:97], v[106:109], v[126:129], v[82:97]
	s_waitcnt lgkmcnt(4)
	v_mfma_f32_32x32x16_bf16 v[82:97], v[110:113], v[134:137], v[82:97]
	s_waitcnt lgkmcnt(3)
	v_mfma_f32_32x32x16_bf16 v[98:113], v[154:157], v[118:121], 0
	s_waitcnt lgkmcnt(2)
	v_mfma_f32_32x32x16_bf16 v[98:113], v[162:165], v[122:125], v[98:113]
	s_waitcnt lgkmcnt(1)
	v_mfma_f32_32x32x16_bf16 v[98:113], v[190:193], v[126:129], v[98:113]
	s_waitcnt lgkmcnt(0)
	v_mfma_f32_32x32x16_bf16 v[98:113], v[206:209], v[134:137], v[98:113]
	s_setprio 0
	s_cbranch_scc1 .LBB0_84
	v_add_u32_e32 v152, s4, v179
	v_cmp_le_i32_e32 vcc, v152, v183
	v_add_u32_e32 v154, 2, v152
	s_nop 7
	v_cndmask_b32_e32 v98, v220, v98, vcc
	v_cmp_lt_i32_e32 vcc, v152, v173
	s_nop 1
	v_cndmask_b32_e32 v83, v220, v83, vcc
	v_cmp_le_i32_e32 vcc, v152, v173
	s_nop 1
	v_cndmask_b32_e32 v82, v220, v82, vcc
	v_cmp_le_i32_e32 vcc, v152, v184
	s_nop 1
	v_cndmask_b32_e32 v99, v220, v99, vcc
	v_cmp_le_i32_e32 vcc, v154, v173
	v_add_u32_e32 v154, 3, v152
	s_nop 0
	v_cndmask_b32_e32 v84, v220, v84, vcc
	v_cmp_le_i32_e32 vcc, v152, v185
	s_nop 1
	v_cndmask_b32_e32 v100, v220, v100, vcc
	v_cmp_le_i32_e32 vcc, v154, v173
	s_nop 1
	v_cndmask_b32_e32 v85, v220, v85, vcc
	v_cmp_le_i32_e32 vcc, v152, v186
	s_nop 1
	v_cndmask_b32_e32 v101, v220, v101, vcc
	v_cmp_le_i32_e32 vcc, v152, v187
	s_nop 1
	v_cndmask_b32_e32 v86, v220, v86, vcc
	v_cmp_le_i32_e32 vcc, v152, v188
	s_nop 1
	v_cndmask_b32_e32 v102, v220, v102, vcc
	v_cmp_le_i32_e32 vcc, v152, v189
	s_nop 1
	v_cndmask_b32_e32 v87, v220, v87, vcc
	v_cmp_le_i32_e32 vcc, v152, v195
	s_nop 1
	v_cndmask_b32_e32 v103, v220, v103, vcc
	v_cmp_le_i32_e32 vcc, v152, v196
	s_nop 1
	v_cndmask_b32_e32 v88, v220, v88, vcc
	v_cmp_le_i32_e32 vcc, v152, v197
	s_nop 1
	v_cndmask_b32_e32 v104, v220, v104, vcc
	v_cmp_le_i32_e32 vcc, v152, v198
	s_nop 1
	v_cndmask_b32_e32 v89, v220, v89, vcc
	v_cmp_le_i32_e32 vcc, v152, v199
	s_nop 1
	v_cndmask_b32_e32 v105, v220, v105, vcc
	v_cmp_le_i32_e32 vcc, v152, v200
	s_nop 1
	v_cndmask_b32_e32 v90, v220, v90, vcc
	v_cmp_le_i32_e32 vcc, v152, v201
	s_nop 1
	v_cndmask_b32_e32 v106, v220, v106, vcc
	v_cmp_le_i32_e32 vcc, v152, v202
	s_nop 1
	v_cndmask_b32_e32 v91, v220, v91, vcc
	v_cmp_le_i32_e32 vcc, v152, v203
	s_nop 1
	v_cndmask_b32_e32 v107, v220, v107, vcc
	v_cmp_le_i32_e32 vcc, v152, v204
	s_nop 1
	v_cndmask_b32_e32 v92, v220, v92, vcc
	v_cmp_le_i32_e32 vcc, v152, v205
	s_nop 1
	v_cndmask_b32_e32 v108, v220, v108, vcc
	v_cmp_le_i32_e32 vcc, v152, v228
	s_nop 1
	v_cndmask_b32_e32 v93, v220, v93, vcc
	v_cmp_le_i32_e32 vcc, v152, v229
	s_nop 1
	v_cndmask_b32_e32 v109, v220, v109, vcc
	v_cmp_le_i32_e32 vcc, v152, v230
	s_nop 1
	v_cndmask_b32_e32 v94, v220, v94, vcc
	v_cmp_le_i32_e32 vcc, v152, v231
	s_nop 1
	v_cndmask_b32_e32 v110, v220, v110, vcc
	v_cmp_le_i32_e32 vcc, v152, v232
	s_nop 1
	v_cndmask_b32_e32 v95, v220, v95, vcc
	v_cmp_le_i32_e32 vcc, v152, v233
	s_nop 1
	v_cndmask_b32_e32 v111, v220, v111, vcc
	v_cmp_le_i32_e32 vcc, v152, v234
	s_nop 1
	v_cndmask_b32_e32 v96, v220, v96, vcc
	v_cmp_le_i32_e32 vcc, v152, v235
	s_nop 1
	v_cndmask_b32_e32 v112, v220, v112, vcc
	v_cmp_le_i32_e32 vcc, v152, v236
	s_nop 1
	v_cndmask_b32_e32 v97, v220, v97, vcc
	v_cmp_le_i32_e32 vcc, v152, v237
	s_nop 1
	v_cndmask_b32_e32 v113, v220, v113, vcc

.LBB0_90:
	v_add3_u32 v153, s26, v182, v181
	s_mov_b32 s78, s76
	s_mov_b32 s79, s76
	s_mov_b32 s77, s76
	ds_read_b64_tr_b16 v[154:155], v153 offset:9216
	ds_read_b64_tr_b16 v[156:157], v153 offset:11776
	ds_read_b64_tr_b16 v[162:163], v153 offset:9280
	ds_read_b64_tr_b16 v[164:165], v153 offset:11840
	ds_read_b64_tr_b16 v[190:191], v153 offset:9344
	ds_read_b64_tr_b16 v[192:193], v153 offset:11904
	ds_read_b64_tr_b16 v[206:207], v153 offset:9408
	ds_read_b64_tr_b16 v[208:209], v153 offset:11968
	v_sub_f32_e32 v82, v82, v152
	v_sub_f32_e32 v83, v83, v152
	v_sub_f32_e32 v84, v84, v152
	v_sub_f32_e32 v85, v85, v152
	v_sub_f32_e32 v86, v86, v152
	v_sub_f32_e32 v87, v87, v152
	v_sub_f32_e32 v88, v88, v152
	v_sub_f32_e32 v89, v89, v152
	v_exp_f32_e32 v82, v82
	v_exp_f32_e32 v83, v83
	v_exp_f32_e32 v84, v84
	v_exp_f32_e32 v85, v85
	v_exp_f32_e32 v86, v86
	v_exp_f32_e32 v87, v87
	v_exp_f32_e32 v88, v88
	v_exp_f32_e32 v89, v89
	v_cvt_pk_bf16_f32 v82, v82, v83
	v_cvt_pk_bf16_f32 v83, v84, v85
	v_cvt_pk_bf16_f32 v84, v86, v87
	v_cvt_pk_bf16_f32 v85, v88, v89
	v_mov_b64_e32 v[88:89], s[78:79]
	v_mov_b64_e32 v[86:87], s[76:77]
	s_setprio 1
	s_waitcnt lgkmcnt(6)
	v_mfma_f32_32x32x16_bf16 v[2:17], v[82:85], v[154:157], v[2:17]
	v_sub_f32_e32 v90, v90, v152
	v_sub_f32_e32 v91, v91, v152
	v_sub_f32_e32 v92, v92, v152
	v_sub_f32_e32 v93, v93, v152
	ds_read_b64_tr_b16 v[154:155], v153 offset:14336
	ds_read_b64_tr_b16 v[156:157], v153 offset:16896
	s_waitcnt lgkmcnt(6)
	v_mfma_f32_32x32x16_bf16 v[50:65], v[82:85], v[162:165], v[50:65]
	v_sub_f32_e32 v94, v94, v152
	v_sub_f32_e32 v95, v95, v152
	v_sub_f32_e32 v96, v96, v152
	v_sub_f32_e32 v97, v97, v152
	ds_read_b64_tr_b16 v[162:163], v153 offset:14400
	ds_read_b64_tr_b16 v[164:165], v153 offset:16960
	s_waitcnt lgkmcnt(6)
	v_mfma_f32_32x32x16_bf16 v[18:33], v[82:85], v[190:193], v[18:33]
	v_exp_f32_e32 v90, v90
	v_exp_f32_e32 v91, v91
	v_exp_f32_e32 v92, v92
	v_exp_f32_e32 v93, v93
	ds_read_b64_tr_b16 v[190:191], v153 offset:14464
	ds_read_b64_tr_b16 v[192:193], v153 offset:17024
	s_waitcnt lgkmcnt(6)
	v_mfma_f32_32x32x16_bf16 v[34:49], v[82:85], v[206:209], v[34:49]
	v_exp_f32_e32 v94, v94
	v_exp_f32_e32 v95, v95
	v_exp_f32_e32 v96, v96
	v_exp_f32_e32 v97, v97
	ds_read_b64_tr_b16 v[206:207], v153 offset:14528
	ds_read_b64_tr_b16 v[208:209], v153 offset:17088
	v_mfma_f32_32x32x16_bf16 v[66:81], v[82:85], v[86:89], v[66:81]
	v_cvt_pk_bf16_f32 v90, v90, v91
	v_cvt_pk_bf16_f32 v91, v92, v93
	v_cvt_pk_bf16_f32 v92, v94, v95
	v_cvt_pk_bf16_f32 v93, v96, v97
	s_nop 0
	s_waitcnt lgkmcnt(6)
	v_mfma_f32_32x32x16_bf16 v[2:17], v[90:93], v[154:157], v[2:17]
	v_sub_f32_e32 v98, v98, v152
	v_sub_f32_e32 v99, v99, v152
	v_sub_f32_e32 v100, v100, v152
	v_sub_f32_e32 v101, v101, v152
	ds_read_b64_tr_b16 v[154:155], v153 offset:19456
	ds_read_b64_tr_b16 v[156:157], v153 offset:22016
	s_waitcnt lgkmcnt(6)
	v_mfma_f32_32x32x16_bf16 v[50:65], v[90:93], v[162:165], v[50:65]
	v_sub_f32_e32 v102, v102, v152
	v_sub_f32_e32 v103, v103, v152
	v_sub_f32_e32 v104, v104, v152
	v_sub_f32_e32 v105, v105, v152
	ds_read_b64_tr_b16 v[162:163], v153 offset:19520
	ds_read_b64_tr_b16 v[164:165], v153 offset:22080
	s_waitcnt lgkmcnt(6)
	v_mfma_f32_32x32x16_bf16 v[18:33], v[90:93], v[190:193], v[18:33]
	v_exp_f32_e32 v98, v98
	v_exp_f32_e32 v99, v99
	v_exp_f32_e32 v100, v100
	v_exp_f32_e32 v101, v101
	ds_read_b64_tr_b16 v[190:191], v153 offset:19584
	ds_read_b64_tr_b16 v[192:193], v153 offset:22144
	s_waitcnt lgkmcnt(6)
	v_mfma_f32_32x32x16_bf16 v[34:49], v[90:93], v[206:209], v[34:49]
	v_exp_f32_e32 v102, v102
	v_exp_f32_e32 v103, v103
	v_exp_f32_e32 v104, v104
	v_exp_f32_e32 v105, v105
	ds_read_b64_tr_b16 v[206:207], v153 offset:19648
	ds_read_b64_tr_b16 v[208:209], v153 offset:22208
	v_mfma_f32_32x32x16_bf16 v[66:81], v[90:93], v[86:89], v[66:81]
	v_cvt_pk_bf16_f32 v98, v98, v99
	v_cvt_pk_bf16_f32 v99, v100, v101
	v_cvt_pk_bf16_f32 v100, v102, v103
	v_cvt_pk_bf16_f32 v101, v104, v105
	s_nop 0
	s_waitcnt lgkmcnt(6)
	v_mfma_f32_32x32x16_bf16 v[2:17], v[98:101], v[154:157], v[2:17]
	v_sub_f32_e32 v106, v106, v152
	v_sub_f32_e32 v107, v107, v152
	v_sub_f32_e32 v108, v108, v152
	v_sub_f32_e32 v109, v109, v152
	ds_read_b64_tr_b16 v[154:155], v153 offset:24576
	ds_read_b64_tr_b16 v[156:157], v153 offset:27136
	s_waitcnt lgkmcnt(6)
	v_mfma_f32_32x32x16_bf16 v[50:65], v[98:101], v[162:165], v[50:65]
	v_sub_f32_e32 v110, v110, v152
	v_sub_f32_e32 v111, v111, v152
	v_sub_f32_e32 v112, v112, v152
	v_sub_f32_e32 v113, v113, v152
	ds_read_b64_tr_b16 v[162:163], v153 offset:24640
	ds_read_b64_tr_b16 v[164:165], v153 offset:27200
	s_waitcnt lgkmcnt(6)
	v_mfma_f32_32x32x16_bf16 v[18:33], v[98:101], v[190:193], v[18:33]
	v_exp_f32_e32 v106, v106
	v_exp_f32_e32 v107, v107
	v_exp_f32_e32 v108, v108
	v_exp_f32_e32 v109, v109
	ds_read_b64_tr_b16 v[190:191], v153 offset:24704
	ds_read_b64_tr_b16 v[192:193], v153 offset:27264
	s_waitcnt lgkmcnt(6)
	v_mfma_f32_32x32x16_bf16 v[34:49], v[98:101], v[206:209], v[34:49]
	v_exp_f32_e32 v110, v110
	v_exp_f32_e32 v111, v111
	v_exp_f32_e32 v112, v112
	v_exp_f32_e32 v113, v113
	ds_read_b64_tr_b16 v[206:207], v153 offset:24768
	ds_read_b64_tr_b16 v[208:209], v153 offset:27328
	v_mfma_f32_32x32x16_bf16 v[66:81], v[98:101], v[86:89], v[66:81]
	v_cvt_pk_bf16_f32 v106, v106, v107
	v_cvt_pk_bf16_f32 v107, v108, v109
	v_cvt_pk_bf16_f32 v108, v110, v111
	v_cvt_pk_bf16_f32 v109, v112, v113
	s_nop 0
	s_waitcnt lgkmcnt(6)
	v_mfma_f32_32x32x16_bf16 v[2:17], v[106:109], v[154:157], v[2:17]
	s_waitcnt lgkmcnt(4)
	v_mfma_f32_32x32x16_bf16 v[50:65], v[106:109], v[162:165], v[50:65]
	s_waitcnt lgkmcnt(2)
	v_mfma_f32_32x32x16_bf16 v[18:33], v[106:109], v[190:193], v[18:33]
	s_waitcnt lgkmcnt(0)
	v_mfma_f32_32x32x16_bf16 v[34:49], v[106:109], v[206:209], v[34:49]
	v_mfma_f32_32x32x16_bf16 v[66:81], v[106:109], v[86:89], v[66:81]
	s_setprio 0
	s_movk_i32 s77, 0x110
	s_andn2_b64 vcc, exec, s[28:29]
	s_cbranch_vccnz .LBB0_92
